# scan loops: lane-select via SALU-shifted mask instead of v_cmp, drop v_mov via op_sel on pk_fma (on top of permlane-free attention)
# baseline (speedup 1.0000x reference)
; template <bool WITH_P, bool FROM_STATE, bool WITH_Y, bool STORE_E>
; DI void scan_unit(LAS unsigned char* lds, const int sq, const int h, const int d, const int seg, const int nseg) {
;     ...
;         float ykq = 0.f;
;     ...
; #pragma unroll 1
;         for (int q = 0; q < 16; ++q) {
.LBB0_600:
	s_mov_b32 s98, 0x1010101
	s_mov_b32 s99, 0x1010101
	v_mov_b32_e32 v62, 0
	s_mov_b32 s19, 0
	v_mov_b32_e32 v60, v112
	v_mov_b32_e32 v61, v110
	s_mov_b32 s35, 0
	s_branch .LBB0_602

; #define LAS __attribute__((address_space(3)))
; template <bool WITH_P, bool FROM_STATE, bool WITH_Y, bool STORE_E>
; DI void scan_unit(LAS unsigned char* lds, const int sq, const int h, const int d, const int seg, const int nseg) {
;     ...
;         for (int q = 0; q < 16; ++q) {
;             f32x2 a2_[2][4], b2_[2][4], k2_[2][4], r2_[2][4]; float vvs[2];
; #pragma unroll
;             for (int ii = 0; ii < 2; ++ii) { const int i = 2 * q + ii;
;                 const f32x4 a_0 = *(const LAS f32x4*)(Aa + i * 64 + 8 * cgp), a_1 = *(const LAS f32x4*)(Aa + i * 64 + 8 * cgp + 4);
;                 const f32x4 b_0 = *(const LAS f32x4*)(Bb + i * 64 + 8 * cgp), b_1 = *(const LAS f32x4*)(Bb + i * 64 + 8 * cgp + 4);
;                 const f32x4 k_0 = *(const LAS f32x4*)(Kd + i * 64 + 8 * cgp), k_1 = *(const LAS f32x4*)(Kd + i * 64 + 8 * cgp + 4);
;                 const f32x4 r_0 = *(const LAS f32x4*)(Rr + i * 64 + 8 * cgp), r_1 = *(const LAS f32x4*)(Rr + i * 64 + 8 * cgp + 4);
;                 vvs[ii] = Vv[i * 64 + row];
;                 a2_[ii][0] = LO2(a_0); a2_[ii][1] = HI2(a_0); a2_[ii][2] = LO2(a_1); a2_[ii][3] = HI2(a_1);
;                 b2_[ii][0] = LO2(b_0); b2_[ii][1] = HI2(b_0); b2_[ii][2] = LO2(b_1); b2_[ii][3] = HI2(b_1);
;                 k2_[ii][0] = LO2(k_0); k2_[ii][1] = HI2(k_0); k2_[ii][2] = LO2(k_1); k2_[ii][3] = HI2(k_1);
;                 r2_[ii][0] = LO2(r_0); r2_[ii][1] = HI2(r_0); r2_[ii][2] = LO2(r_1); r2_[ii][3] = HI2(r_1); }
;             f32x2 s2 = st2[0] * a2_[0][0], p2 = sp2[0] * a2_[0][0];
; #pragma unroll
;             for (int j = 1; j < 4; ++j) { s2 = st2[j] * a2_[0][j] + s2; if (WITH_P) p2 = sp2[j] * a2_[0][j] + p2; }
;             float sa = s2.x + s2.y, pa = p2.x + p2.y;
;             RED3(sa, pa);
;             { const f32x2 sab = {sa, sa}, vvb = {vvs[0], vvs[0]}, pab = {pa, pa};
; #pragma unroll
;               for (int j = 0; j < 4; ++j) { st2[j] = vvb * k2_[0][j] + st2[j]; st2[j] = sab * b2_[0][j] + st2[j]; if (WITH_P) sp2[j] = pab * b2_[0][j] + sp2[j]; } }
;             f32x2 y2 = st2[0] * r2_[0][0]; s2 = st2[0] * a2_[1][0]; p2 = sp2[0] * a2_[1][0];
; #pragma unroll
;             for (int j = 1; j < 4; ++j) { if (WITH_Y) y2 = st2[j] * r2_[0][j] + y2; s2 = st2[j] * a2_[1][j] + s2; if (WITH_P) p2 = sp2[j] * a2_[1][j] + p2; }
;             float y0 = y2.x + y2.y; sa = s2.x + s2.y; pa = p2.x + p2.y;
;             RED3(sa, pa);
.LBB0_602:
	ds_read_b128 v[64:67], v60
	ds_read_b128 v[84:87], v60 offset:16
	ds_read_b128 v[88:91], v60 offset:8192
	ds_read_b128 v[92:95], v60 offset:8208
	ds_read_b128 v[96:99], v60 offset:16384
	ds_read_b128 v[114:117], v60 offset:16400
	ds_read_b128 v[118:121], v60 offset:24576
	ds_read_b128 v[122:125], v60 offset:24592
	ds_read2st64_b32 v[158:159], v61 offset1:1
	ds_read_b128 v[126:129], v60 offset:256
	ds_read_b128 v[130:133], v60 offset:272
	ds_read_b128 v[134:137], v60 offset:8448
	ds_read_b128 v[138:141], v60 offset:8464
	ds_read_b128 v[142:145], v60 offset:16640
	ds_read_b128 v[146:149], v60 offset:16656
	ds_read_b128 v[150:153], v60 offset:24832
	ds_read_b128 v[154:157], v60 offset:24848
	s_waitcnt lgkmcnt(14)
	v_pk_mul_f32 v[66:67], v[58:59], v[66:67]
	s_waitcnt lgkmcnt(8)
	v_pk_fma_f32 v[58:59], v[98:99], v[158:159], v[58:59] op_sel_hi:[1,0,1]
	v_pk_fma_f32 v[64:65], v[56:57], v[64:65], v[66:67]
	v_pk_fma_f32 v[56:57], v[96:97], v[158:159], v[56:57] op_sel_hi:[1,0,1]
	v_pk_fma_f32 v[64:65], v[0:1], v[84:85], v[64:65]
	v_pk_fma_f32 v[0:1], v[114:115], v[158:159], v[0:1] op_sel_hi:[1,0,1]
	v_pk_fma_f32 v[64:65], v[2:3], v[86:87], v[64:65]
	v_pk_fma_f32 v[2:3], v[116:117], v[158:159], v[2:3] op_sel_hi:[1,0,1]
	v_add_f32_e32 v63, v64, v65
	s_and_b32 s48, s19, 6
	s_lshl_b64 s[100:101], s[98:99], s48
	v_add_f32_dpp v63, v63, v63 quad_perm:[1,0,3,2] row_mask:0xf bank_mask:0xf bound_ctrl:1
	s_or_b32 s48, s48, 1
	s_and_b32 s49, s35, 3
	v_add_f32_dpp v63, v63, v63 quad_perm:[2,3,0,1] row_mask:0xf bank_mask:0xf bound_ctrl:1
	s_nop 0
	v_add_f32_dpp v64, v63, v63 row_half_mirror row_mask:0xf bank_mask:0xf bound_ctrl:1
	v_pk_fma_f32 v[58:59], v[90:91], v[64:65], v[58:59] op_sel_hi:[1,0,1]
	v_pk_fma_f32 v[56:57], v[88:89], v[64:65], v[56:57] op_sel_hi:[1,0,1]
	v_pk_fma_f32 v[0:1], v[92:93], v[64:65], v[0:1] op_sel_hi:[1,0,1]
	v_pk_fma_f32 v[2:3], v[94:95], v[64:65], v[2:3] op_sel_hi:[1,0,1]
	v_pk_mul_f32 v[64:65], v[120:121], v[58:59]
	s_waitcnt lgkmcnt(7)
	v_pk_mul_f32 v[66:67], v[128:129], v[58:59]
	v_pk_fma_f32 v[64:65], v[118:119], v[56:57], v[64:65]
	v_pk_fma_f32 v[66:67], v[126:127], v[56:57], v[66:67]
	v_pk_fma_f32 v[64:65], v[122:123], v[0:1], v[64:65]
	s_waitcnt lgkmcnt(6)
	v_pk_fma_f32 v[66:67], v[130:131], v[0:1], v[66:67]
	v_pk_fma_f32 v[64:65], v[124:125], v[2:3], v[64:65]
	v_pk_fma_f32 v[66:67], v[132:133], v[2:3], v[66:67]
	v_add_f32_e32 v63, v64, v65
	v_add_f32_e32 v64, v66, v67
	s_waitcnt lgkmcnt(3)
	v_pk_fma_f32 v[58:59], v[144:145], v[158:159], v[58:59] op_sel:[0,1,0] op_sel_hi:[1,1,1]
	v_add_f32_dpp v64, v64, v64 quad_perm:[1,0,3,2] row_mask:0xf bank_mask:0xf bound_ctrl:1
	v_pk_fma_f32 v[56:57], v[142:143], v[158:159], v[56:57] op_sel:[0,1,0] op_sel_hi:[1,1,1]
	s_waitcnt lgkmcnt(2)
	v_pk_fma_f32 v[0:1], v[146:147], v[158:159], v[0:1] op_sel:[0,1,0] op_sel_hi:[1,1,1]
	v_add_f32_dpp v64, v64, v64 quad_perm:[2,3,0,1] row_mask:0xf bank_mask:0xf bound_ctrl:1
	v_pk_fma_f32 v[2:3], v[148:149], v[158:159], v[2:3] op_sel:[0,1,0] op_sel_hi:[1,1,1]
	v_add_f32_dpp v63, v63, v63 quad_perm:[1,0,3,2] row_mask:0xf bank_mask:0xf bound_ctrl:1
	v_add_f32_dpp v64, v64, v64 row_half_mirror row_mask:0xf bank_mask:0xf bound_ctrl:1
	v_pk_fma_f32 v[58:59], v[136:137], v[64:65], v[58:59] op_sel_hi:[1,0,1]
	v_pk_fma_f32 v[56:57], v[134:135], v[64:65], v[56:57] op_sel_hi:[1,0,1]
	v_pk_fma_f32 v[0:1], v[138:139], v[64:65], v[0:1] op_sel_hi:[1,0,1]
	v_pk_fma_f32 v[2:3], v[140:141], v[64:65], v[2:3] op_sel_hi:[1,0,1]
	s_waitcnt lgkmcnt(1)
	v_pk_mul_f32 v[64:65], v[152:153], v[58:59]
	v_add_f32_dpp v63, v63, v63 quad_perm:[2,3,0,1] row_mask:0xf bank_mask:0xf bound_ctrl:1
	v_pk_fma_f32 v[64:65], v[150:151], v[56:57], v[64:65]
	s_waitcnt lgkmcnt(0)
	v_pk_fma_f32 v[64:65], v[154:155], v[0:1], v[64:65]
	v_add_f32_dpp v63, v63, v63 row_half_mirror row_mask:0xf bank_mask:0xf bound_ctrl:1
	v_pk_fma_f32 v[64:65], v[156:157], v[2:3], v[64:65]
	v_cndmask_b32_e64 v62, v62, v63, s[100:101]
	v_add_f32_e32 v63, v64, v65
	s_lshl_b64 s[100:101], s[98:99], s48
	s_cmp_lg_u32 s49, 3
	s_nop 0
	v_add_f32_dpp v63, v63, v63 quad_perm:[1,0,3,2] row_mask:0xf bank_mask:0xf bound_ctrl:1
	s_nop 1
	v_add_f32_dpp v63, v63, v63 quad_perm:[2,3,0,1] row_mask:0xf bank_mask:0xf bound_ctrl:1
	s_nop 1
	v_add_f32_dpp v63, v63, v63 row_half_mirror row_mask:0xf bank_mask:0xf bound_ctrl:1
	v_cndmask_b32_e64 v62, v62, v63, s[100:101]
	s_cbranch_scc1 .LBB0_601
	v_and_or_b32 v63, s19, 24, v101
	v_lshl_add_u32 v63, v63, 8, v107
	ds_write_b32 v63, v62
	s_branch .LBB0_601

; template <bool WITH_P, bool FROM_STATE, bool WITH_Y, bool STORE_E>
; DI void scan_unit(LAS unsigned char* lds, const int sq, const int h, const int d, const int seg, const int nseg) {
;     ...
;         float ykq = 0.f;
;     ...
; #pragma unroll 1
;         for (int q = 0; q < 16; ++q) {
.LBB0_687:
	s_mov_b32 s98, 0x1010101
	s_mov_b32 s99, 0x1010101
	v_mov_b32_e32 v62, 0
	s_mov_b32 s17, 0
	v_mov_b32_e32 v60, v111
	v_mov_b32_e32 v61, v110
	s_mov_b32 s27, 0
	s_branch .LBB0_689

; #define LAS __attribute__((address_space(3)))
; template <bool WITH_P, bool FROM_STATE, bool WITH_Y, bool STORE_E>
; DI void scan_unit(LAS unsigned char* lds, const int sq, const int h, const int d, const int seg, const int nseg) {
;     ...
;         for (int q = 0; q < 16; ++q) {
;             f32x2 a2_[2][4], b2_[2][4], k2_[2][4], r2_[2][4]; float vvs[2];
; #pragma unroll
;             for (int ii = 0; ii < 2; ++ii) { const int i = 2 * q + ii;
;                 const f32x4 a_0 = *(const LAS f32x4*)(Aa + i * 64 + 8 * cgp), a_1 = *(const LAS f32x4*)(Aa + i * 64 + 8 * cgp + 4);
;                 const f32x4 b_0 = *(const LAS f32x4*)(Bb + i * 64 + 8 * cgp), b_1 = *(const LAS f32x4*)(Bb + i * 64 + 8 * cgp + 4);
;                 const f32x4 k_0 = *(const LAS f32x4*)(Kd + i * 64 + 8 * cgp), k_1 = *(const LAS f32x4*)(Kd + i * 64 + 8 * cgp + 4);
;                 const f32x4 r_0 = *(const LAS f32x4*)(Rr + i * 64 + 8 * cgp), r_1 = *(const LAS f32x4*)(Rr + i * 64 + 8 * cgp + 4);
;                 vvs[ii] = Vv[i * 64 + row];
;                 a2_[ii][0] = LO2(a_0); a2_[ii][1] = HI2(a_0); a2_[ii][2] = LO2(a_1); a2_[ii][3] = HI2(a_1);
;                 b2_[ii][0] = LO2(b_0); b2_[ii][1] = HI2(b_0); b2_[ii][2] = LO2(b_1); b2_[ii][3] = HI2(b_1);
;                 k2_[ii][0] = LO2(k_0); k2_[ii][1] = HI2(k_0); k2_[ii][2] = LO2(k_1); k2_[ii][3] = HI2(k_1);
;                 r2_[ii][0] = LO2(r_0); r2_[ii][1] = HI2(r_0); r2_[ii][2] = LO2(r_1); r2_[ii][3] = HI2(r_1); }
;             f32x2 s2 = st2[0] * a2_[0][0], p2 = sp2[0] * a2_[0][0];
; #pragma unroll
;             for (int j = 1; j < 4; ++j) { s2 = st2[j] * a2_[0][j] + s2; if (WITH_P) p2 = sp2[j] * a2_[0][j] + p2; }
;             float sa = s2.x + s2.y, pa = p2.x + p2.y;
;             RED3(sa, pa);
;             { const f32x2 sab = {sa, sa}, vvb = {vvs[0], vvs[0]}, pab = {pa, pa};
; #pragma unroll
;               for (int j = 0; j < 4; ++j) { st2[j] = vvb * k2_[0][j] + st2[j]; st2[j] = sab * b2_[0][j] + st2[j]; if (WITH_P) sp2[j] = pab * b2_[0][j] + sp2[j]; } }
;             f32x2 y2 = st2[0] * r2_[0][0]; s2 = st2[0] * a2_[1][0]; p2 = sp2[0] * a2_[1][0];
; #pragma unroll
;             for (int j = 1; j < 4; ++j) { if (WITH_Y) y2 = st2[j] * r2_[0][j] + y2; s2 = st2[j] * a2_[1][j] + s2; if (WITH_P) p2 = sp2[j] * a2_[1][j] + p2; }
;             float y0 = y2.x + y2.y; sa = s2.x + s2.y; pa = p2.x + p2.y;
;             RED3(sa, pa);
.LBB0_689:
	ds_read_b128 v[64:67], v60
	ds_read_b128 v[80:83], v60 offset:16
	ds_read_b128 v[84:87], v60 offset:8192
	ds_read_b128 v[88:91], v60 offset:8208
	ds_read_b128 v[92:95], v60 offset:16384
	ds_read_b128 v[114:117], v60 offset:16400
	ds_read_b128 v[118:121], v60 offset:24576
	ds_read_b128 v[122:125], v60 offset:24592
	ds_read2st64_b32 v[158:159], v61 offset1:1
	ds_read_b128 v[126:129], v60 offset:256
	ds_read_b128 v[130:133], v60 offset:272
	ds_read_b128 v[134:137], v60 offset:8448
	ds_read_b128 v[138:141], v60 offset:8464
	ds_read_b128 v[142:145], v60 offset:16640
	ds_read_b128 v[146:149], v60 offset:16656
	ds_read_b128 v[150:153], v60 offset:24832
	ds_read_b128 v[154:157], v60 offset:24848
	s_waitcnt lgkmcnt(14)
	v_pk_mul_f32 v[66:67], v[38:39], v[66:67]
	s_waitcnt lgkmcnt(8)
	v_pk_fma_f32 v[38:39], v[94:95], v[158:159], v[38:39] op_sel_hi:[1,0,1]
	v_pk_fma_f32 v[64:65], v[36:37], v[64:65], v[66:67]
	v_pk_fma_f32 v[36:37], v[92:93], v[158:159], v[36:37] op_sel_hi:[1,0,1]
	v_pk_fma_f32 v[64:65], v[40:41], v[80:81], v[64:65]
	v_pk_fma_f32 v[40:41], v[114:115], v[158:159], v[40:41] op_sel_hi:[1,0,1]
	v_pk_fma_f32 v[64:65], v[42:43], v[82:83], v[64:65]
	v_pk_fma_f32 v[42:43], v[116:117], v[158:159], v[42:43] op_sel_hi:[1,0,1]
	v_add_f32_e32 v63, v64, v65
	s_and_b32 s34, s17, 6
	s_lshl_b64 s[100:101], s[98:99], s34
	v_add_f32_dpp v63, v63, v63 quad_perm:[1,0,3,2] row_mask:0xf bank_mask:0xf bound_ctrl:1
	s_or_b32 s34, s34, 1
	s_and_b32 s35, s27, 3
	v_add_f32_dpp v63, v63, v63 quad_perm:[2,3,0,1] row_mask:0xf bank_mask:0xf bound_ctrl:1
	s_nop 0
	v_add_f32_dpp v64, v63, v63 row_half_mirror row_mask:0xf bank_mask:0xf bound_ctrl:1
	v_pk_fma_f32 v[38:39], v[86:87], v[64:65], v[38:39] op_sel_hi:[1,0,1]
	v_pk_fma_f32 v[36:37], v[84:85], v[64:65], v[36:37] op_sel_hi:[1,0,1]
	v_pk_fma_f32 v[40:41], v[88:89], v[64:65], v[40:41] op_sel_hi:[1,0,1]
	v_pk_fma_f32 v[42:43], v[90:91], v[64:65], v[42:43] op_sel_hi:[1,0,1]
	v_pk_mul_f32 v[64:65], v[120:121], v[38:39]
	s_waitcnt lgkmcnt(7)
	v_pk_mul_f32 v[66:67], v[128:129], v[38:39]
	v_pk_fma_f32 v[64:65], v[118:119], v[36:37], v[64:65]
	v_pk_fma_f32 v[66:67], v[126:127], v[36:37], v[66:67]
	v_pk_fma_f32 v[64:65], v[122:123], v[40:41], v[64:65]
	s_waitcnt lgkmcnt(6)
	v_pk_fma_f32 v[66:67], v[130:131], v[40:41], v[66:67]
	v_pk_fma_f32 v[64:65], v[124:125], v[42:43], v[64:65]
	v_pk_fma_f32 v[66:67], v[132:133], v[42:43], v[66:67]
	v_add_f32_e32 v63, v64, v65
	v_add_f32_e32 v64, v66, v67
	s_waitcnt lgkmcnt(3)
	v_pk_fma_f32 v[38:39], v[144:145], v[158:159], v[38:39] op_sel:[0,1,0] op_sel_hi:[1,1,1]
	v_add_f32_dpp v64, v64, v64 quad_perm:[1,0,3,2] row_mask:0xf bank_mask:0xf bound_ctrl:1
	v_pk_fma_f32 v[36:37], v[142:143], v[158:159], v[36:37] op_sel:[0,1,0] op_sel_hi:[1,1,1]
	s_waitcnt lgkmcnt(2)
	v_pk_fma_f32 v[40:41], v[146:147], v[158:159], v[40:41] op_sel:[0,1,0] op_sel_hi:[1,1,1]
	v_add_f32_dpp v64, v64, v64 quad_perm:[2,3,0,1] row_mask:0xf bank_mask:0xf bound_ctrl:1
	v_pk_fma_f32 v[42:43], v[148:149], v[158:159], v[42:43] op_sel:[0,1,0] op_sel_hi:[1,1,1]
	v_add_f32_dpp v63, v63, v63 quad_perm:[1,0,3,2] row_mask:0xf bank_mask:0xf bound_ctrl:1
	v_add_f32_dpp v64, v64, v64 row_half_mirror row_mask:0xf bank_mask:0xf bound_ctrl:1
	v_pk_fma_f32 v[38:39], v[136:137], v[64:65], v[38:39] op_sel_hi:[1,0,1]
	v_pk_fma_f32 v[36:37], v[134:135], v[64:65], v[36:37] op_sel_hi:[1,0,1]
	v_pk_fma_f32 v[40:41], v[138:139], v[64:65], v[40:41] op_sel_hi:[1,0,1]
	v_pk_fma_f32 v[42:43], v[140:141], v[64:65], v[42:43] op_sel_hi:[1,0,1]
	s_waitcnt lgkmcnt(1)
	v_pk_mul_f32 v[64:65], v[152:153], v[38:39]
	v_add_f32_dpp v63, v63, v63 quad_perm:[2,3,0,1] row_mask:0xf bank_mask:0xf bound_ctrl:1
	v_pk_fma_f32 v[64:65], v[150:151], v[36:37], v[64:65]
	s_waitcnt lgkmcnt(0)
	v_pk_fma_f32 v[64:65], v[154:155], v[40:41], v[64:65]
	v_add_f32_dpp v63, v63, v63 row_half_mirror row_mask:0xf bank_mask:0xf bound_ctrl:1
	v_pk_fma_f32 v[64:65], v[156:157], v[42:43], v[64:65]
	v_cndmask_b32_e64 v62, v62, v63, s[100:101]
	v_add_f32_e32 v63, v64, v65
	s_lshl_b64 s[100:101], s[98:99], s34
	s_cmp_lg_u32 s35, 3
	s_nop 0
	v_add_f32_dpp v63, v63, v63 quad_perm:[1,0,3,2] row_mask:0xf bank_mask:0xf bound_ctrl:1
	s_nop 1
	v_add_f32_dpp v63, v63, v63 quad_perm:[2,3,0,1] row_mask:0xf bank_mask:0xf bound_ctrl:1
	s_nop 1
	v_add_f32_dpp v63, v63, v63 row_half_mirror row_mask:0xf bank_mask:0xf bound_ctrl:1
	v_cndmask_b32_e64 v62, v62, v63, s[100:101]
	s_cbranch_scc1 .LBB0_688
	v_and_or_b32 v63, s17, 24, v96
	v_lshl_add_u32 v63, v63, 8, v105
	ds_write_b32 v63, v62
	s_branch .LBB0_688
